# ph9-rope-table-loads-pipelined-one-group-ahead
# speedup vs baseline: 1.0478x; 1.0038x over previous
.LBB0_435:
	s_lshl_b32 s42, 1, s29
	v_readlane_b32 s43, v250, 22
	s_and_b32 s42, s42, s43
	s_cmp_lg_u32 s42, 0
	s_cselect_b64 s[42:43], -1, 0
	s_and_b64 s[42:43], s[58:59], s[42:43]
	s_and_b64 s[64:65], s[36:37], s[42:43]
	v_pk_mul_f32 v[150:151], v[62:63], v[96:97] op_sel_hi:[1,0]
	v_pk_mul_f32 v[148:149], v[60:61], v[96:97] op_sel_hi:[1,0]
	v_pk_mul_f32 v[136:137], v[50:51], v[96:97] op_sel_hi:[1,0]
	v_pk_mul_f32 v[140:141], v[48:49], v[96:97] op_sel_hi:[1,0]
	v_pk_mul_f32 v[142:143], v[38:39], v[96:97] op_sel_hi:[1,0]
	v_pk_mul_f32 v[138:139], v[36:37], v[96:97] op_sel_hi:[1,0]
	v_pk_mul_f32 v[144:145], v[34:35], v[96:97] op_sel_hi:[1,0]
	v_pk_mul_f32 v[146:147], v[32:33], v[96:97] op_sel_hi:[1,0]
	s_and_saveexec_b64 s[42:43], s[64:65]
	s_cbranch_execz .LBB0_437
	v_lshlrev_b64 v[32:33], 7, v[132:133]
	v_lshl_add_u64 v[36:37], s[72:73], 0, v[32:33]
	global_load_dwordx4 v[32:35], v[36:37], off offset:16
	s_nop 0
	global_load_dwordx4 v[36:39], v[36:37], off
	v_lshlrev_b32_e32 v192, 7, v132
	v_add_u32_e32 v192, 0x800, v192
	v_mov_b32_e32 v158, v192
	global_load_dwordx4 v[192:195], v192, s[72:73] offset:16
	global_load_dwordx4 v[158:161], v158, s[72:73]
	s_waitcnt vmcnt(2)
	v_mul_f32_e32 v62, v136, v33
	v_mov_b32_e32 v48, v36
	v_mov_b32_e32 v49, v38
	v_mov_b32_e32 v38, v37
	v_mul_f32_e32 v98, v136, v32
	v_mov_b32_e32 v136, v151
	v_pk_mul_f32 v[36:37], v[140:141], v[38:39]
	v_pk_mul_f32 v[50:51], v[140:141], v[48:49]
	v_pk_mul_f32 v[140:141], v[136:137], v[34:35]
	v_mul_f32_e32 v60, v150, v32
	v_mul_f32_e32 v134, v150, v33
	v_mov_b32_e32 v61, v140
	v_mov_b32_e32 v63, v141
	v_mov_b32_e32 v150, v137
	v_pk_add_f32 v[60:61], v[60:61], v[62:63] neg_lo:[0,1] neg_hi:[0,1]
	v_pk_mul_f32 v[62:63], v[150:151], v[34:35]
	v_pk_fma_f32 v[36:37], v[148:149], v[48:49], v[36:37] neg_lo:[0,0,1] neg_hi:[0,0,1]
	v_mov_b32_e32 v135, v63
	v_mov_b32_e32 v99, v62
	v_pk_add_f32 v[136:137], v[134:135], v[98:99]
	v_mul_f32_e32 v98, v142, v32
	v_mul_f32_e32 v134, v144, v33
	v_mul_f32_e32 v32, v144, v32
	v_mov_b32_e32 v144, v143
	v_pk_fma_f32 v[140:141], v[148:149], v[38:39], v[50:51]
	v_pk_mul_f32 v[50:51], v[146:147], v[38:39]
	v_pk_mul_f32 v[62:63], v[146:147], v[48:49]
	v_mul_f32_e32 v148, v142, v33
	v_pk_mul_f32 v[146:147], v[144:145], v[34:35]
	v_mov_b32_e32 v142, v145
	v_mov_b32_e32 v99, v146
	v_mov_b32_e32 v135, v147
	v_pk_mul_f32 v[34:35], v[142:143], v[34:35]
	v_pk_fma_f32 v[48:49], v[138:139], v[48:49], v[50:51] neg_lo:[0,0,1] neg_hi:[0,0,1]
	v_pk_add_f32 v[50:51], v[98:99], v[134:135] neg_lo:[0,1] neg_hi:[0,1]
	v_mov_b32_e32 v149, v35
	v_mov_b32_e32 v33, v34
	v_pk_fma_f32 v[146:147], v[138:139], v[38:39], v[62:63]
	v_pk_add_f32 v[144:145], v[148:149], v[32:33]
	v_mov_b32_e32 v138, v48
	v_mov_b32_e32 v139, v49
	v_mov_b32_e32 v142, v50
	v_mov_b32_e32 v143, v51
	v_mov_b32_e32 v148, v36
	v_mov_b32_e32 v149, v37
	v_mov_b32_e32 v150, v60
	v_mov_b32_e32 v151, v61

.LBB0_443:
	v_pk_mul_f32 v[130:131], v[130:131], v[96:97] op_sel_hi:[1,0]
	v_pk_mul_f32 v[128:129], v[128:129], v[96:97] op_sel_hi:[1,0]
	v_pk_mul_f32 v[126:127], v[126:127], v[96:97] op_sel_hi:[1,0]
	v_pk_mul_f32 v[124:125], v[124:125], v[96:97] op_sel_hi:[1,0]
	v_pk_mul_f32 v[122:123], v[122:123], v[96:97] op_sel_hi:[1,0]
	v_pk_mul_f32 v[120:121], v[120:121], v[96:97] op_sel_hi:[1,0]
	v_pk_mul_f32 v[118:119], v[118:119], v[96:97] op_sel_hi:[1,0]
	v_pk_mul_f32 v[116:117], v[116:117], v[96:97] op_sel_hi:[1,0]
	s_and_saveexec_b64 s[30:31], s[64:65]
	s_cbranch_execz .LBB0_445
	v_lshlrev_b64 v[138:139], 7, v[136:137]
	v_lshl_add_u64 v[142:143], s[72:73], 0, v[138:139]
	s_waitcnt vmcnt(2)
	v_mov_b32_e32 v138, v192
	v_mov_b32_e32 v139, v193
	v_mov_b32_e32 v140, v194
	v_mov_b32_e32 v141, v195
	v_mov_b32_e32 v142, v158
	v_mov_b32_e32 v143, v159
	v_mov_b32_e32 v144, v160
	v_mov_b32_e32 v145, v161
	v_lshlrev_b32_e32 v192, 7, v132
	v_add_u32_e32 v192, 0x1000, v192
	v_mov_b32_e32 v158, v192
	global_load_dwordx4 v[192:195], v192, s[72:73] offset:16
	global_load_dwordx4 v[158:161], v158, s[72:73]
	v_mul_f32_e32 v150, v126, v139
	v_mul_f32_e32 v152, v126, v138
	v_mov_b32_e32 v126, v131
	v_mul_f32_e32 v148, v130, v138
	v_mul_f32_e32 v154, v130, v139
	v_pk_mul_f32 v[156:157], v[126:127], v[140:141]
	v_mov_b32_e32 v130, v127
	v_mov_b32_e32 v149, v156
	v_mov_b32_e32 v151, v157
	v_pk_mul_f32 v[126:127], v[130:131], v[140:141]
	v_mov_b32_e32 v146, v142
	v_mov_b32_e32 v147, v144
	v_mov_b32_e32 v144, v143
	v_pk_add_f32 v[148:149], v[148:149], v[150:151] neg_lo:[0,1] neg_hi:[0,1]
	v_mov_b32_e32 v155, v127
	v_mov_b32_e32 v153, v126
	v_mul_f32_e32 v130, v122, v138
	v_mul_f32_e32 v150, v118, v139
	v_mul_f32_e32 v138, v118, v138
	v_mov_b32_e32 v118, v123
	v_pk_mul_f32 v[142:143], v[124:125], v[144:145]
	v_pk_mul_f32 v[124:125], v[124:125], v[146:147]
	v_pk_add_f32 v[126:127], v[154:155], v[152:153]
	v_mul_f32_e32 v152, v122, v139
	v_pk_mul_f32 v[154:155], v[118:119], v[140:141]
	v_mov_b32_e32 v122, v119
	v_pk_fma_f32 v[142:143], v[128:129], v[146:147], v[142:143] neg_lo:[0,0,1] neg_hi:[0,0,1]
	v_pk_fma_f32 v[124:125], v[128:129], v[144:145], v[124:125]
	v_pk_mul_f32 v[128:129], v[116:117], v[144:145]
	v_mov_b32_e32 v131, v154
	v_mov_b32_e32 v151, v155
	v_pk_mul_f32 v[118:119], v[122:123], v[140:141]
	v_pk_mul_f32 v[116:117], v[116:117], v[146:147]
	v_pk_fma_f32 v[128:129], v[120:121], v[146:147], v[128:129] neg_lo:[0,0,1] neg_hi:[0,0,1]
	v_pk_add_f32 v[130:131], v[130:131], v[150:151] neg_lo:[0,1] neg_hi:[0,1]
	v_mov_b32_e32 v153, v119
	v_mov_b32_e32 v139, v118
	v_pk_fma_f32 v[116:117], v[120:121], v[144:145], v[116:117]
	v_pk_add_f32 v[118:119], v[152:153], v[138:139]
	v_mov_b32_e32 v120, v128
	v_mov_b32_e32 v121, v129
	v_mov_b32_e32 v122, v130
	v_mov_b32_e32 v123, v131
	v_mov_b32_e32 v128, v142
	v_mov_b32_e32 v129, v143
	v_mov_b32_e32 v130, v148
	v_mov_b32_e32 v131, v149

.LBB0_450:
	v_pk_mul_f32 v[114:115], v[114:115], v[96:97] op_sel_hi:[1,0]
	v_pk_mul_f32 v[112:113], v[112:113], v[96:97] op_sel_hi:[1,0]
	v_pk_mul_f32 v[110:111], v[110:111], v[96:97] op_sel_hi:[1,0]
	v_pk_mul_f32 v[108:109], v[108:109], v[96:97] op_sel_hi:[1,0]
	v_pk_mul_f32 v[106:107], v[106:107], v[96:97] op_sel_hi:[1,0]
	v_pk_mul_f32 v[104:105], v[104:105], v[96:97] op_sel_hi:[1,0]
	v_pk_mul_f32 v[102:103], v[102:103], v[96:97] op_sel_hi:[1,0]
	v_pk_mul_f32 v[100:101], v[100:101], v[96:97] op_sel_hi:[1,0]
	s_and_saveexec_b64 s[30:31], s[64:65]
	s_cbranch_execz .LBB0_452
	v_lshlrev_b64 v[118:119], 7, v[116:117]
	v_lshl_add_u64 v[122:123], s[72:73], 0, v[118:119]
	s_waitcnt vmcnt(2)
	v_mov_b32_e32 v118, v192
	v_mov_b32_e32 v119, v193
	v_mov_b32_e32 v120, v194
	v_mov_b32_e32 v121, v195
	v_mov_b32_e32 v122, v158
	v_mov_b32_e32 v123, v159
	v_mov_b32_e32 v124, v160
	v_mov_b32_e32 v125, v161
	v_lshlrev_b32_e32 v192, 7, v132
	v_add_u32_e32 v192, 0x1800, v192
	v_mov_b32_e32 v158, v192
	global_load_dwordx4 v[192:195], v192, s[72:73] offset:16
	global_load_dwordx4 v[158:161], v158, s[72:73]
	v_mul_f32_e32 v130, v110, v119
	v_mul_f32_e32 v136, v110, v118
	v_mov_b32_e32 v110, v115
	v_mul_f32_e32 v128, v114, v118
	v_mul_f32_e32 v138, v114, v119
	v_pk_mul_f32 v[140:141], v[110:111], v[120:121]
	v_mov_b32_e32 v114, v111
	v_mov_b32_e32 v129, v140
	v_mov_b32_e32 v131, v141
	v_pk_mul_f32 v[110:111], v[114:115], v[120:121]
	v_mov_b32_e32 v126, v122
	v_mov_b32_e32 v127, v124
	v_mov_b32_e32 v124, v123
	v_pk_add_f32 v[128:129], v[128:129], v[130:131] neg_lo:[0,1] neg_hi:[0,1]
	v_mov_b32_e32 v139, v111
	v_mov_b32_e32 v137, v110
	v_mul_f32_e32 v114, v106, v118
	v_mul_f32_e32 v130, v102, v119
	v_mul_f32_e32 v118, v102, v118
	v_mov_b32_e32 v102, v107
	v_pk_mul_f32 v[122:123], v[108:109], v[124:125]
	v_pk_mul_f32 v[108:109], v[108:109], v[126:127]
	v_pk_add_f32 v[110:111], v[138:139], v[136:137]
	v_mul_f32_e32 v136, v106, v119
	v_pk_mul_f32 v[138:139], v[102:103], v[120:121]
	v_mov_b32_e32 v106, v103
	v_pk_fma_f32 v[122:123], v[112:113], v[126:127], v[122:123] neg_lo:[0,0,1] neg_hi:[0,0,1]
	v_pk_fma_f32 v[108:109], v[112:113], v[124:125], v[108:109]
	v_pk_mul_f32 v[112:113], v[100:101], v[124:125]
	v_mov_b32_e32 v115, v138
	v_mov_b32_e32 v131, v139
	v_pk_mul_f32 v[102:103], v[106:107], v[120:121]
	v_pk_mul_f32 v[100:101], v[100:101], v[126:127]
	v_pk_fma_f32 v[112:113], v[104:105], v[126:127], v[112:113] neg_lo:[0,0,1] neg_hi:[0,0,1]
	v_pk_add_f32 v[114:115], v[114:115], v[130:131] neg_lo:[0,1] neg_hi:[0,1]
	v_mov_b32_e32 v137, v103
	v_mov_b32_e32 v119, v102
	v_pk_fma_f32 v[100:101], v[104:105], v[124:125], v[100:101]
	v_pk_add_f32 v[102:103], v[136:137], v[118:119]
	v_mov_b32_e32 v104, v112
	v_mov_b32_e32 v105, v113
	v_mov_b32_e32 v106, v114
	v_mov_b32_e32 v107, v115
	v_mov_b32_e32 v112, v122
	v_mov_b32_e32 v113, v123
	v_mov_b32_e32 v114, v128
	v_mov_b32_e32 v115, v129

.LBB0_457:
	v_pk_mul_f32 v[94:95], v[94:95], v[96:97] op_sel_hi:[1,0]
	v_pk_mul_f32 v[92:93], v[92:93], v[96:97] op_sel_hi:[1,0]
	v_pk_mul_f32 v[90:91], v[90:91], v[96:97] op_sel_hi:[1,0]
	v_pk_mul_f32 v[88:89], v[88:89], v[96:97] op_sel_hi:[1,0]
	v_pk_mul_f32 v[86:87], v[86:87], v[96:97] op_sel_hi:[1,0]
	v_pk_mul_f32 v[84:85], v[84:85], v[96:97] op_sel_hi:[1,0]
	v_pk_mul_f32 v[82:83], v[82:83], v[96:97] op_sel_hi:[1,0]
	v_pk_mul_f32 v[80:81], v[80:81], v[96:97] op_sel_hi:[1,0]
	s_and_saveexec_b64 s[30:31], s[64:65]
	s_cbranch_execz .LBB0_459
	v_lshlrev_b64 v[102:103], 7, v[100:101]
	v_lshl_add_u64 v[106:107], s[72:73], 0, v[102:103]
	s_waitcnt vmcnt(2)
	v_mov_b32_e32 v102, v192
	v_mov_b32_e32 v103, v193
	v_mov_b32_e32 v104, v194
	v_mov_b32_e32 v105, v195
	v_mov_b32_e32 v106, v158
	v_mov_b32_e32 v107, v159
	v_mov_b32_e32 v108, v160
	v_mov_b32_e32 v109, v161
	v_lshlrev_b32_e32 v192, 7, v132
	v_add_u32_e32 v192, 0x4000, v192
	v_mov_b32_e32 v158, v192
	global_load_dwordx4 v[192:195], v192, s[72:73] offset:16
	global_load_dwordx4 v[158:161], v158, s[72:73]
	v_mul_f32_e32 v114, v90, v103
	v_mul_f32_e32 v116, v90, v102
	v_mov_b32_e32 v90, v95
	v_mul_f32_e32 v112, v94, v102
	v_mul_f32_e32 v118, v94, v103
	v_pk_mul_f32 v[120:121], v[90:91], v[104:105]
	v_mov_b32_e32 v94, v91
	v_mov_b32_e32 v113, v120
	v_mov_b32_e32 v115, v121
	v_pk_mul_f32 v[90:91], v[94:95], v[104:105]
	v_mov_b32_e32 v110, v106
	v_mov_b32_e32 v111, v108
	v_mov_b32_e32 v108, v107
	v_pk_add_f32 v[112:113], v[112:113], v[114:115] neg_lo:[0,1] neg_hi:[0,1]
	v_mov_b32_e32 v119, v91
	v_mov_b32_e32 v117, v90
	v_mul_f32_e32 v94, v86, v102
	v_mul_f32_e32 v114, v82, v103
	v_mul_f32_e32 v102, v82, v102
	v_mov_b32_e32 v82, v87
	v_pk_mul_f32 v[106:107], v[88:89], v[108:109]
	v_pk_mul_f32 v[88:89], v[88:89], v[110:111]
	v_pk_add_f32 v[90:91], v[118:119], v[116:117]
	v_mul_f32_e32 v116, v86, v103
	v_pk_mul_f32 v[118:119], v[82:83], v[104:105]
	v_mov_b32_e32 v86, v83
	v_pk_fma_f32 v[106:107], v[92:93], v[110:111], v[106:107] neg_lo:[0,0,1] neg_hi:[0,0,1]
	v_pk_fma_f32 v[88:89], v[92:93], v[108:109], v[88:89]
	v_pk_mul_f32 v[92:93], v[80:81], v[108:109]
	v_mov_b32_e32 v95, v118
	v_mov_b32_e32 v115, v119
	v_pk_mul_f32 v[82:83], v[86:87], v[104:105]
	v_pk_mul_f32 v[80:81], v[80:81], v[110:111]
	v_pk_fma_f32 v[92:93], v[84:85], v[110:111], v[92:93] neg_lo:[0,0,1] neg_hi:[0,0,1]
	v_pk_add_f32 v[94:95], v[94:95], v[114:115] neg_lo:[0,1] neg_hi:[0,1]
	v_mov_b32_e32 v117, v83
	v_mov_b32_e32 v103, v82
	v_pk_fma_f32 v[80:81], v[84:85], v[108:109], v[80:81]
	v_pk_add_f32 v[82:83], v[116:117], v[102:103]
	v_mov_b32_e32 v84, v92
	v_mov_b32_e32 v85, v93
	v_mov_b32_e32 v86, v94
	v_mov_b32_e32 v87, v95
	v_mov_b32_e32 v92, v106
	v_mov_b32_e32 v93, v107
	v_mov_b32_e32 v94, v112
	v_mov_b32_e32 v95, v113

.LBB0_464:
	v_pk_mul_f32 v[84:85], v[66:67], v[86:87] op_sel_hi:[1,0]
	v_pk_mul_f32 v[82:83], v[64:65], v[86:87] op_sel_hi:[1,0]
	v_pk_mul_f32 v[64:65], v[78:79], v[86:87] op_sel_hi:[1,0]
	v_pk_mul_f32 v[76:77], v[76:77], v[86:87] op_sel_hi:[1,0]
	v_pk_mul_f32 v[74:75], v[74:75], v[86:87] op_sel_hi:[1,0]
	v_pk_mul_f32 v[66:67], v[72:73], v[86:87] op_sel_hi:[1,0]
	v_pk_mul_f32 v[70:71], v[70:71], v[86:87] op_sel_hi:[1,0]
	v_pk_mul_f32 v[68:69], v[68:69], v[86:87] op_sel_hi:[1,0]
	s_and_saveexec_b64 s[30:31], s[64:65]
	s_cbranch_execz .LBB0_466
	v_lshlrev_b64 v[72:73], 7, v[80:81]
	v_lshl_add_u64 v[72:73], s[72:73], 0, v[72:73]
	s_waitcnt vmcnt(2)
	v_mov_b32_e32 v86, v192
	v_mov_b32_e32 v87, v193
	v_mov_b32_e32 v88, v194
	v_mov_b32_e32 v89, v195
	v_mov_b32_e32 v90, v158
	v_mov_b32_e32 v91, v159
	v_mov_b32_e32 v92, v160
	v_mov_b32_e32 v93, v161
	v_lshlrev_b32_e32 v192, 7, v132
	v_add_u32_e32 v192, 0x4800, v192
	v_mov_b32_e32 v158, v192
	global_load_dwordx4 v[192:195], v192, s[72:73] offset:16
	global_load_dwordx4 v[158:161], v158, s[72:73]
	v_mul_f32_e32 v94, v64, v87
	v_mul_f32_e32 v100, v64, v86
	v_mov_b32_e32 v64, v85
	v_mov_b32_e32 v72, v90
	v_mul_f32_e32 v90, v84, v86
	v_mul_f32_e32 v102, v84, v87
	v_pk_mul_f32 v[104:105], v[64:65], v[88:89]
	v_mov_b32_e32 v84, v65
	v_mov_b32_e32 v73, v92
	v_mov_b32_e32 v92, v91
	v_mov_b32_e32 v91, v104
	v_mov_b32_e32 v95, v105
	v_pk_mul_f32 v[64:65], v[84:85], v[88:89]
	v_pk_add_f32 v[90:91], v[90:91], v[94:95] neg_lo:[0,1] neg_hi:[0,1]
	v_mov_b32_e32 v103, v65
	v_mov_b32_e32 v101, v64
	v_mul_f32_e32 v84, v74, v86
	v_mul_f32_e32 v94, v70, v87
	v_mul_f32_e32 v86, v70, v86
	v_mov_b32_e32 v70, v75
	v_pk_mul_f32 v[78:79], v[76:77], v[92:93]
	v_pk_mul_f32 v[76:77], v[76:77], v[72:73]
	v_pk_add_f32 v[64:65], v[102:103], v[100:101]
	v_mul_f32_e32 v100, v74, v87
	v_pk_mul_f32 v[102:103], v[70:71], v[88:89]
	v_mov_b32_e32 v74, v71
	v_pk_fma_f32 v[78:79], v[82:83], v[72:73], v[78:79] neg_lo:[0,0,1] neg_hi:[0,0,1]
	v_pk_fma_f32 v[76:77], v[82:83], v[92:93], v[76:77]
	v_pk_mul_f32 v[82:83], v[68:69], v[92:93]
	v_mov_b32_e32 v85, v102
	v_mov_b32_e32 v95, v103
	v_pk_mul_f32 v[70:71], v[74:75], v[88:89]
	v_pk_mul_f32 v[68:69], v[68:69], v[72:73]
	v_pk_fma_f32 v[72:73], v[66:67], v[72:73], v[82:83] neg_lo:[0,0,1] neg_hi:[0,0,1]
	v_pk_add_f32 v[82:83], v[84:85], v[94:95] neg_lo:[0,1] neg_hi:[0,1]
	v_mov_b32_e32 v101, v71
	v_mov_b32_e32 v87, v70
	v_pk_fma_f32 v[68:69], v[66:67], v[92:93], v[68:69]
	v_pk_add_f32 v[70:71], v[100:101], v[86:87]
	v_mov_b32_e32 v66, v72
	v_mov_b32_e32 v67, v73
	v_mov_b32_e32 v74, v82
	v_mov_b32_e32 v75, v83
	v_mov_b32_e32 v82, v78
	v_mov_b32_e32 v83, v79
	v_mov_b32_e32 v84, v90
	v_mov_b32_e32 v85, v91

.LBB0_471:
	v_pk_mul_f32 v[58:59], v[58:59], v[66:67] op_sel_hi:[1,0]
	v_pk_mul_f32 v[56:57], v[56:57], v[66:67] op_sel_hi:[1,0]
	v_pk_mul_f32 v[54:55], v[54:55], v[66:67] op_sel_hi:[1,0]
	v_pk_mul_f32 v[52:53], v[52:53], v[66:67] op_sel_hi:[1,0]
	v_pk_mul_f32 v[46:47], v[46:47], v[66:67] op_sel_hi:[1,0]
	v_pk_mul_f32 v[44:45], v[44:45], v[66:67] op_sel_hi:[1,0]
	v_pk_mul_f32 v[42:43], v[42:43], v[66:67] op_sel_hi:[1,0]
	v_pk_mul_f32 v[40:41], v[40:41], v[66:67] op_sel_hi:[1,0]
	s_and_saveexec_b64 s[30:31], s[64:65]
	s_cbranch_execz .LBB0_473
	v_lshlrev_b64 v[66:67], 7, v[64:65]
	v_lshl_add_u64 v[70:71], s[72:73], 0, v[66:67]
	s_waitcnt vmcnt(2)
	v_mov_b32_e32 v66, v192
	v_mov_b32_e32 v67, v193
	v_mov_b32_e32 v68, v194
	v_mov_b32_e32 v69, v195
	v_mov_b32_e32 v70, v158
	v_mov_b32_e32 v71, v159
	v_mov_b32_e32 v72, v160
	v_mov_b32_e32 v73, v161
	v_lshlrev_b32_e32 v192, 7, v132
	v_add_u32_e32 v192, 0x5000, v192
	v_mov_b32_e32 v158, v192
	global_load_dwordx4 v[192:195], v192, s[72:73] offset:16
	global_load_dwordx4 v[158:161], v158, s[72:73]
	v_mul_f32_e32 v78, v54, v67
	v_mul_f32_e32 v80, v54, v66
	v_mov_b32_e32 v54, v59
	v_mul_f32_e32 v76, v58, v66
	v_mul_f32_e32 v82, v58, v67
	v_pk_mul_f32 v[84:85], v[54:55], v[68:69]
	v_mov_b32_e32 v58, v55
	v_mov_b32_e32 v77, v84
	v_mov_b32_e32 v79, v85
	v_pk_mul_f32 v[54:55], v[58:59], v[68:69]
	v_mov_b32_e32 v74, v70
	v_mov_b32_e32 v75, v72
	v_mov_b32_e32 v72, v71
	v_pk_add_f32 v[76:77], v[76:77], v[78:79] neg_lo:[0,1] neg_hi:[0,1]
	v_mov_b32_e32 v83, v55
	v_mov_b32_e32 v81, v54
	v_mul_f32_e32 v58, v46, v66
	v_mul_f32_e32 v78, v42, v67
	v_mul_f32_e32 v66, v42, v66
	v_mov_b32_e32 v42, v47
	v_pk_mul_f32 v[70:71], v[52:53], v[72:73]
	v_pk_mul_f32 v[52:53], v[52:53], v[74:75]
	v_pk_add_f32 v[54:55], v[82:83], v[80:81]
	v_mul_f32_e32 v80, v46, v67
	v_pk_mul_f32 v[82:83], v[42:43], v[68:69]
	v_mov_b32_e32 v46, v43
	v_pk_fma_f32 v[70:71], v[56:57], v[74:75], v[70:71] neg_lo:[0,0,1] neg_hi:[0,0,1]
	v_pk_fma_f32 v[52:53], v[56:57], v[72:73], v[52:53]
	v_pk_mul_f32 v[56:57], v[40:41], v[72:73]
	v_mov_b32_e32 v59, v82
	v_mov_b32_e32 v79, v83
	v_pk_mul_f32 v[42:43], v[46:47], v[68:69]
	v_pk_mul_f32 v[40:41], v[40:41], v[74:75]
	v_pk_fma_f32 v[56:57], v[44:45], v[74:75], v[56:57] neg_lo:[0,0,1] neg_hi:[0,0,1]
	v_pk_add_f32 v[58:59], v[58:59], v[78:79] neg_lo:[0,1] neg_hi:[0,1]
	v_mov_b32_e32 v81, v43
	v_mov_b32_e32 v67, v42
	v_pk_fma_f32 v[40:41], v[44:45], v[72:73], v[40:41]
	v_pk_add_f32 v[42:43], v[80:81], v[66:67]
	v_mov_b32_e32 v44, v56
	v_mov_b32_e32 v45, v57
	v_mov_b32_e32 v46, v58
	v_mov_b32_e32 v47, v59
	v_mov_b32_e32 v56, v70
	v_mov_b32_e32 v57, v71
	v_mov_b32_e32 v58, v76
	v_mov_b32_e32 v59, v77

.LBB0_478:
	v_pk_mul_f32 v[30:31], v[30:31], v[42:43] op_sel_hi:[1,0]
	v_pk_mul_f32 v[28:29], v[28:29], v[42:43] op_sel_hi:[1,0]
	v_pk_mul_f32 v[26:27], v[26:27], v[42:43] op_sel_hi:[1,0]
	v_pk_mul_f32 v[24:25], v[24:25], v[42:43] op_sel_hi:[1,0]
	v_pk_mul_f32 v[22:23], v[22:23], v[42:43] op_sel_hi:[1,0]
	v_pk_mul_f32 v[20:21], v[20:21], v[42:43] op_sel_hi:[1,0]
	v_pk_mul_f32 v[18:19], v[18:19], v[42:43] op_sel_hi:[1,0]
	v_pk_mul_f32 v[16:17], v[16:17], v[42:43] op_sel_hi:[1,0]
	s_and_saveexec_b64 s[30:31], s[64:65]
	s_cbranch_execz .LBB0_480
	v_lshlrev_b64 v[42:43], 7, v[40:41]
	v_lshl_add_u64 v[46:47], s[72:73], 0, v[42:43]
	s_waitcnt vmcnt(2)
	v_mov_b32_e32 v42, v192
	v_mov_b32_e32 v43, v193
	v_mov_b32_e32 v44, v194
	v_mov_b32_e32 v45, v195
	v_mov_b32_e32 v52, v158
	v_mov_b32_e32 v53, v159
	v_mov_b32_e32 v54, v160
	v_mov_b32_e32 v55, v161
	v_lshlrev_b32_e32 v192, 7, v132
	v_add_u32_e32 v192, 0x5800, v192
	v_mov_b32_e32 v158, v192
	global_load_dwordx4 v[192:195], v192, s[72:73] offset:16
	global_load_dwordx4 v[158:161], v158, s[72:73]
	v_mul_f32_e32 v58, v26, v43
	v_mul_f32_e32 v64, v26, v42
	v_mov_b32_e32 v26, v31
	v_mul_f32_e32 v56, v30, v42
	v_mul_f32_e32 v66, v30, v43
	v_pk_mul_f32 v[68:69], v[26:27], v[44:45]
	v_mov_b32_e32 v30, v27
	v_mov_b32_e32 v57, v68
	v_mov_b32_e32 v59, v69
	v_pk_mul_f32 v[26:27], v[30:31], v[44:45]
	v_mov_b32_e32 v46, v52
	v_mov_b32_e32 v47, v54
	v_mov_b32_e32 v54, v53
	v_pk_add_f32 v[56:57], v[56:57], v[58:59] neg_lo:[0,1] neg_hi:[0,1]
	v_mov_b32_e32 v67, v27
	v_mov_b32_e32 v65, v26
	v_mul_f32_e32 v30, v22, v42
	v_mul_f32_e32 v58, v18, v43
	v_mul_f32_e32 v42, v18, v42
	v_mov_b32_e32 v18, v23
	v_pk_mul_f32 v[52:53], v[24:25], v[54:55]
	v_pk_mul_f32 v[24:25], v[24:25], v[46:47]
	v_pk_add_f32 v[26:27], v[66:67], v[64:65]
	v_mul_f32_e32 v64, v22, v43
	v_pk_mul_f32 v[66:67], v[18:19], v[44:45]
	v_mov_b32_e32 v22, v19
	v_pk_fma_f32 v[52:53], v[28:29], v[46:47], v[52:53] neg_lo:[0,0,1] neg_hi:[0,0,1]
	v_pk_fma_f32 v[24:25], v[28:29], v[54:55], v[24:25]
	v_pk_mul_f32 v[28:29], v[16:17], v[54:55]
	v_mov_b32_e32 v31, v66
	v_mov_b32_e32 v59, v67
	v_pk_mul_f32 v[18:19], v[22:23], v[44:45]
	v_pk_mul_f32 v[16:17], v[16:17], v[46:47]
	v_pk_fma_f32 v[28:29], v[20:21], v[46:47], v[28:29] neg_lo:[0,0,1] neg_hi:[0,0,1]
	v_pk_add_f32 v[30:31], v[30:31], v[58:59] neg_lo:[0,1] neg_hi:[0,1]
	v_mov_b32_e32 v65, v19
	v_mov_b32_e32 v43, v18
	v_pk_fma_f32 v[16:17], v[20:21], v[54:55], v[16:17]
	v_pk_add_f32 v[18:19], v[64:65], v[42:43]
	v_mov_b32_e32 v20, v28
	v_mov_b32_e32 v21, v29
	v_mov_b32_e32 v22, v30
	v_mov_b32_e32 v23, v31
	v_mov_b32_e32 v28, v52
	v_mov_b32_e32 v29, v53
	v_mov_b32_e32 v30, v56
	v_mov_b32_e32 v31, v57

.LBB0_485:
	v_pk_mul_f32 v[14:15], v[14:15], v[18:19] op_sel_hi:[1,0]
	v_pk_mul_f32 v[12:13], v[12:13], v[18:19] op_sel_hi:[1,0]
	v_pk_mul_f32 v[10:11], v[10:11], v[18:19] op_sel_hi:[1,0]
	v_pk_mul_f32 v[8:9], v[8:9], v[18:19] op_sel_hi:[1,0]
	v_pk_mul_f32 v[6:7], v[6:7], v[18:19] op_sel_hi:[1,0]
	v_pk_mul_f32 v[4:5], v[4:5], v[18:19] op_sel_hi:[1,0]
	v_pk_mul_f32 v[2:3], v[2:3], v[18:19] op_sel_hi:[1,0]
	v_pk_mul_f32 v[0:1], v[0:1], v[18:19] op_sel_hi:[1,0]
	s_and_saveexec_b64 s[30:31], s[64:65]
	s_cbranch_execz .LBB0_487
	v_lshlrev_b64 v[18:19], 7, v[16:17]
	v_lshl_add_u64 v[22:23], s[72:73], 0, v[18:19]
	s_waitcnt vmcnt(2)
	v_mov_b32_e32 v18, v192
	v_mov_b32_e32 v19, v193
	v_mov_b32_e32 v20, v194
	v_mov_b32_e32 v21, v195
	v_mov_b32_e32 v22, v158
	v_mov_b32_e32 v23, v159
	v_mov_b32_e32 v24, v160
	v_mov_b32_e32 v25, v161
	v_mul_f32_e32 v30, v10, v19
	v_mul_f32_e32 v40, v10, v18
	v_mov_b32_e32 v10, v15
	v_mul_f32_e32 v28, v14, v18
	v_mul_f32_e32 v42, v14, v19
	v_pk_mul_f32 v[44:45], v[10:11], v[20:21]
	v_mov_b32_e32 v14, v11
	v_mov_b32_e32 v29, v44
	v_mov_b32_e32 v31, v45
	v_pk_mul_f32 v[10:11], v[14:15], v[20:21]
	v_mov_b32_e32 v26, v22
	v_mov_b32_e32 v27, v24
	v_mov_b32_e32 v24, v23
	v_pk_add_f32 v[28:29], v[28:29], v[30:31] neg_lo:[0,1] neg_hi:[0,1]
	v_mov_b32_e32 v43, v11
	v_mov_b32_e32 v41, v10
	v_mul_f32_e32 v14, v6, v18
	v_mul_f32_e32 v30, v2, v19
	v_mul_f32_e32 v18, v2, v18
	v_mov_b32_e32 v2, v7
	v_pk_mul_f32 v[22:23], v[8:9], v[24:25]
	v_pk_mul_f32 v[8:9], v[8:9], v[26:27]
	v_pk_add_f32 v[10:11], v[42:43], v[40:41]
	v_mul_f32_e32 v40, v6, v19
	v_pk_mul_f32 v[42:43], v[2:3], v[20:21]
	v_mov_b32_e32 v6, v3
	v_pk_fma_f32 v[22:23], v[12:13], v[26:27], v[22:23] neg_lo:[0,0,1] neg_hi:[0,0,1]
	v_pk_fma_f32 v[8:9], v[12:13], v[24:25], v[8:9]
	v_pk_mul_f32 v[12:13], v[0:1], v[24:25]
	v_mov_b32_e32 v15, v42
	v_mov_b32_e32 v31, v43
	v_pk_mul_f32 v[2:3], v[6:7], v[20:21]
	v_pk_mul_f32 v[0:1], v[0:1], v[26:27]
	v_pk_fma_f32 v[12:13], v[4:5], v[26:27], v[12:13] neg_lo:[0,0,1] neg_hi:[0,0,1]
	v_pk_add_f32 v[14:15], v[14:15], v[30:31] neg_lo:[0,1] neg_hi:[0,1]
	v_mov_b32_e32 v41, v3
	v_mov_b32_e32 v19, v2
	v_pk_fma_f32 v[0:1], v[4:5], v[24:25], v[0:1]
	v_pk_add_f32 v[2:3], v[40:41], v[18:19]
	v_mov_b32_e32 v4, v12
	v_mov_b32_e32 v5, v13
	v_mov_b32_e32 v6, v14
	v_mov_b32_e32 v7, v15
	v_mov_b32_e32 v12, v22
	v_mov_b32_e32 v13, v23
	v_mov_b32_e32 v14, v28
	v_mov_b32_e32 v15, v29
